# v10: v8 + adaLN-norm phase (layer-input norm) row-0 finish: 12 gamma/scale/shift loads in flight instead of 4 serialized triples
# baseline (speedup 1.0000x reference)
; DI void norm_finish(float4 (&v)[4], const NormRow& r, const float* gam, int sh_off, int sc_off, half_t* h, const float* part, float* xc_store, int lane) {
;     ...
;   float ss = 0.f;
; #pragma unroll
;   for (int i = 0; i < 4; ++i) ss += v[i].x * v[i].x + v[i].y * v[i].y + v[i].z * v[i].z + v[i].w * v[i].w;
;   ss = wave_sum(ss);
;   if (!r.valid) return;
;   const float rstd = rsqrtf(ss * (1.f / 1024.f) + EPS);
; #pragma unroll
;   for (int i = 0; i < 4; ++i) {
;     const int col = i * 256 + lane * 4;
;     const float4 gg = *(const float4*)(gam + col);
;     const float4 sc = *(const float4*)(r.mod + sc_off + col);
;     const float4 sh = *(const float4*)(r.mod + sh_off + col);
;     h4 o;
;     o[0] = (half_t)(v[i].x * rstd * gg.x * (1.f + sc.x) + sh.x);
;     o[1] = (half_t)(v[i].y * rstd * gg.y * (1.f + sc.y) + sh.y);
;     o[2] = (half_t)(v[i].z * rstd * gg.z * (1.f + sc.z) + sh.z);
;     o[3] = (half_t)(v[i].w * rstd * gg.w * (1.f + sc.w) + sh.w);
;     *(h4*)(h + (size_t)r.g * 1024 + col) = o;
;   }
.LBB0_1434:
	s_or_b64 exec, exec, s[12:13]
	v_mul_hi_i32_i24_e32 v1, 0x1800, v60
	v_mul_i32_i24_e32 v51, 0x1800, v60
	v_cndmask_b32_e64 v61, v1, 0, s[6:7]
	v_cndmask_b32_e64 v60, v51, v232, s[6:7]
	s_waitcnt vmcnt(0)
	v_mov_b32_e32 v64, v30
	v_mov_b32_e32 v65, v27
	v_lshl_add_u64 v[62:63], v[60:61], 2, s[38:39]
	v_pk_mov_b32 v[60:61], v[30:31], v[26:27] op_sel:[1,0]
	v_pk_mul_f32 v[64:65], v[64:65], v[64:65]
	v_mov_b32_e32 v66, v23
	v_pk_fma_f32 v[60:61], v[60:61], v[60:61], v[64:65]
	v_mov_b32_e32 v64, v32
	v_mov_b32_e32 v65, v28
	v_pk_fma_f32 v[60:61], v[64:65], v[64:65], v[60:61]
	v_mov_b32_e32 v64, v33
	v_mov_b32_e32 v65, v29
	v_mov_b32_e32 v67, v19
	v_pk_fma_f32 v[60:61], v[64:65], v[64:65], v[60:61]
	v_mov_b32_e32 v64, v22
	v_mov_b32_e32 v65, v18
	v_pk_mul_f32 v[66:67], v[66:67], v[66:67]
	v_add_f32_e32 v1, v60, v61
	v_pk_fma_f32 v[64:65], v[64:65], v[64:65], v[66:67]
	v_mov_b32_e32 v66, v24
	v_mov_b32_e32 v67, v20
	v_pk_fma_f32 v[64:65], v[66:67], v[66:67], v[64:65]
	v_mov_b32_e32 v66, v25
	v_mov_b32_e32 v67, v21
	v_pk_fma_f32 v[64:65], v[66:67], v[66:67], v[64:65]
	s_mov_b64 s[6:7], 0x1000
	v_add_f32_e32 v1, v1, v64
	v_add_f32_e32 v1, v1, v65
	ds_bpermute_b32 v51, v41, v1
	v_lshl_add_u64 v[64:65], v[62:63], 0, s[6:7]
	s_and_b64 s[6:7], s[36:37], s[2:3]
	s_and_b64 s[12:13], s[4:5], s[6:7]
	s_waitcnt lgkmcnt(0)
	v_add_f32_e32 v1, v1, v51
	ds_bpermute_b32 v51, v43, v1
	s_waitcnt lgkmcnt(0)
	v_add_f32_e32 v1, v1, v51
	ds_bpermute_b32 v51, v45, v1
	s_waitcnt lgkmcnt(0)
	v_add_f32_e32 v1, v1, v51
	ds_bpermute_b32 v51, v70, v1
	s_waitcnt lgkmcnt(0)
	v_add_f32_e32 v1, v1, v51
	ds_bpermute_b32 v51, v71, v1
	s_waitcnt lgkmcnt(0)
	v_add_f32_e32 v1, v1, v51
	ds_bpermute_b32 v51, v72, v1
	s_waitcnt lgkmcnt(0)
	v_add_f32_e32 v1, v1, v51
	v_fmamk_f32 v1, v1, 0x3a800000, v222
	v_cmp_gt_f32_e32 vcc, s73, v1
	v_mul_f32_e32 v51, 0x4b800000, v1
	s_nop 0
	v_cndmask_b32_e32 v1, v1, v51, vcc
	v_rsq_f32_e32 v1, v1
	s_nop 0
	v_mul_f32_e32 v51, 0x45800000, v1
	v_cndmask_b32_e32 v60, v1, v51, vcc
	v_mov_b32_e32 v51, v0
	v_lshl_add_u64 v[76:77], v[64:65], 0, v[50:51]
	v_lshl_add_u64 v[62:63], v[62:63], 0, v[50:51]
	global_load_dwordx4 v[144:147], v[38:39], off
	global_load_dwordx4 v[160:163], v[76:77], off
	global_load_dwordx4 v[176:179], v[62:63], off
	global_load_dwordx4 v[148:151], v[38:39], off offset:1024
	global_load_dwordx4 v[164:167], v[76:77], off offset:1024
	global_load_dwordx4 v[180:183], v[62:63], off offset:1024
	global_load_dwordx4 v[152:155], v[38:39], off offset:2048
	global_load_dwordx4 v[168:171], v[76:77], off offset:2048
	global_load_dwordx4 v[184:187], v[62:63], off offset:2048
	global_load_dwordx4 v[156:159], v[38:39], off offset:3072
	global_load_dwordx4 v[172:175], v[76:77], off offset:3072
	global_load_dwordx4 v[188:191], v[62:63], off offset:3072
	s_nop 0
	s_nop 0
	v_pk_mul_f32 v[30:31], v[30:31], v[60:61] op_sel_hi:[1,0]
	v_pk_mul_f32 v[32:33], v[32:33], v[60:61] op_sel_hi:[1,0]
	v_pk_mul_f32 v[26:27], v[26:27], v[60:61] op_sel_hi:[1,0]
	v_pk_mul_f32 v[28:29], v[28:29], v[60:61] op_sel_hi:[1,0]
	v_pk_mul_f32 v[22:23], v[22:23], v[60:61] op_sel_hi:[1,0]
	v_pk_mul_f32 v[24:25], v[24:25], v[60:61] op_sel_hi:[1,0]
	v_pk_mul_f32 v[18:19], v[18:19], v[60:61] op_sel_hi:[1,0]
	v_pk_mul_f32 v[20:21], v[20:21], v[60:61] op_sel_hi:[1,0]
	s_waitcnt vmcnt(0)
	v_pk_mul_f32 v[30:31], v[144:145], v[30:31]
	v_pk_add_f32 v[144:145], v[160:161], 1.0 op_sel_hi:[1,0]
	v_pk_mul_f32 v[32:33], v[146:147], v[32:33]
	v_pk_fma_f32 v[30:31], v[144:145], v[30:31], v[176:177]
	v_pk_add_f32 v[144:145], v[162:163], 1.0 op_sel_hi:[1,0]
	v_cvt_pk_f16_f32 v30, v30, v31
	v_pk_fma_f32 v[32:33], v[144:145], v[32:33], v[178:179]
	s_nop 0
	v_cvt_pk_f16_f32 v31, v32, v33
	global_store_dwordx2 v[48:49], v[30:31], off
	v_lshlrev_b32_e32 v30, 2, v40
	v_mov_b32_e32 v31, v0
	v_lshl_add_u64 v[32:33], v[64:65], 0, v[30:31]
	v_pk_mul_f32 v[26:27], v[26:27], v[148:149]
	v_pk_add_f32 v[32:33], v[164:165], 1.0 op_sel_hi:[1,0]
	v_pk_mul_f32 v[28:29], v[28:29], v[150:151]
	v_pk_fma_f32 v[26:27], v[26:27], v[32:33], v[180:181]
	v_pk_add_f32 v[32:33], v[166:167], 1.0 op_sel_hi:[1,0]
	v_cvt_pk_f16_f32 v26, v26, v27
	v_pk_fma_f32 v[28:29], v[28:29], v[32:33], v[182:183]
	s_nop 0
	v_cvt_pk_f16_f32 v27, v28, v29
	global_store_dwordx2 v[48:49], v[26:27], off offset:512
	v_lshlrev_b32_e32 v26, 2, v42
	v_mov_b32_e32 v27, v0
	v_lshl_add_u64 v[28:29], v[64:65], 0, v[26:27]
	v_pk_mul_f32 v[22:23], v[22:23], v[152:153]
	v_pk_add_f32 v[28:29], v[168:169], 1.0 op_sel_hi:[1,0]
	v_pk_mul_f32 v[24:25], v[24:25], v[154:155]
	v_pk_fma_f32 v[22:23], v[22:23], v[28:29], v[184:185]
	v_pk_add_f32 v[28:29], v[170:171], 1.0 op_sel_hi:[1,0]
	v_cvt_pk_f16_f32 v22, v22, v23
	v_pk_fma_f32 v[24:25], v[24:25], v[28:29], v[186:187]
	s_nop 0
	v_cvt_pk_f16_f32 v23, v24, v25
	global_store_dwordx2 v[48:49], v[22:23], off offset:1024
	v_lshlrev_b32_e32 v22, 2, v44
	v_mov_b32_e32 v23, v0
	v_lshl_add_u64 v[24:25], v[64:65], 0, v[22:23]
	v_pk_mul_f32 v[18:19], v[18:19], v[156:157]
	v_pk_add_f32 v[24:25], v[172:173], 1.0 op_sel_hi:[1,0]
	v_pk_mul_f32 v[20:21], v[20:21], v[158:159]
	v_pk_fma_f32 v[18:19], v[18:19], v[24:25], v[188:189]
	v_pk_add_f32 v[24:25], v[174:175], 1.0 op_sel_hi:[1,0]
	v_cvt_pk_f16_f32 v18, v18, v19
	v_pk_fma_f32 v[20:21], v[20:21], v[24:25], v[190:191]
	s_nop 0
	v_cvt_pk_f16_f32 v19, v20, v21
	global_store_dwordx2 v[48:49], v[18:19], off offset:1536
	s_and_saveexec_b64 s[6:7], s[12:13]
	s_cbranch_execz .LBB0_1436
; DI void norm_finish(float4 (&v)[4], const NormRow& r, const float* gam, int sh_off, int sc_off, half_t* h, const float* part, float* xc_store, int lane) {
;   if (r.valid && r.isctx && part != nullptr) {
;     const size_t ro = ((size_t)r.b * CTX + (r.t - SEQ)) * 1024;
; #pragma unroll
;     for (int i = 0; i < 4; ++i) {
; #pragma unroll
;       for (int ks = 0; ks < 4; ++ks) {
;         const float4 pv = *(const float4*)(part + (size_t)ks * NB * CTX * 1024 + ro + i * 256 + lane * 4);
;         v[i].x += pv.x; v[i].y += pv.y; v[i].z += pv.z; v[i].w += pv.w;
;       }
;       if (xc_store != nullptr) *(float4*)(xc_store + ro + i * 256 + lane * 4) = v[i];
;     }
;   }
	v_mov_b32_e32 v59, v0
	v_lshlrev_b64 v[18:19], 12, v[58:59]
	v_lshl_add_u64 v[18:19], v[36:37], 0, v[18:19]
	v_lshlrev_b64 v[20:21], 20, v[56:57]
	v_lshl_add_u64 v[28:29], v[18:19], 0, v[20:21]
	v_add_co_u32_e32 v24, vcc, 0x1000000, v28
	global_load_dwordx4 v[58:61], v[28:29], off
	s_nop 0
	v_addc_co_u32_e32 v25, vcc, 0, v29, vcc
	v_add_co_u32_e32 v20, vcc, 0x2000000, v28
	global_load_dwordx4 v[62:65], v[24:25], off
	s_nop 0
	v_addc_co_u32_e32 v21, vcc, 0, v29, vcc
	global_load_dwordx4 v[66:69], v[20:21], off
	v_add_co_u32_e32 v18, vcc, 0x3000000, v28
	s_waitcnt vmcnt(2)
	v_pk_add_f32 v[10:11], v[10:11], v[58:59]
	v_pk_add_f32 v[12:13], v[12:13], v[60:61]
	global_load_dwordx4 v[58:61], v[28:29], off offset:1024
	v_addc_co_u32_e32 v19, vcc, 0, v29, vcc
	s_waitcnt vmcnt(2)
	v_pk_add_f32 v[10:11], v[10:11], v[62:63]
	v_pk_add_f32 v[12:13], v[12:13], v[64:65]
	global_load_dwordx4 v[62:65], v[24:25], off offset:1024
	global_load_dwordx4 v[76:79], v[18:19], off
	s_waitcnt vmcnt(3)
	v_pk_add_f32 v[10:11], v[10:11], v[66:67]
	v_pk_add_f32 v[12:13], v[12:13], v[68:69]
	global_load_dwordx4 v[66:69], v[20:21], off offset:1024
	s_waitcnt vmcnt(3)
	v_pk_add_f32 v[6:7], v[6:7], v[58:59]
	v_pk_add_f32 v[8:9], v[8:9], v[60:61]
	global_load_dwordx4 v[58:61], v[28:29], off offset:2048
	s_waitcnt vmcnt(3)
	v_pk_add_f32 v[6:7], v[6:7], v[62:63]
	v_pk_add_f32 v[8:9], v[8:9], v[64:65]
	global_load_dwordx4 v[62:65], v[24:25], off offset:2048
	s_waitcnt vmcnt(3)
	v_pk_add_f32 v[10:11], v[10:11], v[76:77]
	v_pk_add_f32 v[12:13], v[12:13], v[78:79]
	global_load_dwordx4 v[76:79], v[18:19], off offset:1024
	s_waitcnt vmcnt(3)
	v_pk_add_f32 v[6:7], v[6:7], v[66:67]
	v_pk_add_f32 v[8:9], v[8:9], v[68:69]
	global_load_dwordx4 v[66:69], v[20:21], off offset:2048
	s_waitcnt vmcnt(3)
	v_pk_add_f32 v[2:3], v[2:3], v[58:59]
	v_pk_add_f32 v[4:5], v[4:5], v[60:61]
	global_load_dwordx4 v[58:61], v[28:29], off offset:3072
	s_waitcnt vmcnt(3)
	v_pk_add_f32 v[2:3], v[2:3], v[62:63]
	v_pk_add_f32 v[4:5], v[4:5], v[64:65]
	global_load_dwordx4 v[62:65], v[24:25], off offset:3072
	s_waitcnt vmcnt(3)
	v_pk_add_f32 v[6:7], v[6:7], v[76:77]
	v_pk_add_f32 v[8:9], v[8:9], v[78:79]
	global_load_dwordx4 v[76:79], v[18:19], off offset:2048
	s_waitcnt vmcnt(3)
	v_pk_add_f32 v[2:3], v[2:3], v[66:67]
	v_pk_add_f32 v[4:5], v[4:5], v[68:69]
	global_load_dwordx4 v[66:69], v[20:21], off offset:3072
	s_waitcnt vmcnt(3)
	v_pk_add_f32 v[14:15], v[14:15], v[58:59]
	global_load_dwordx4 v[18:21], v[18:19], off offset:3072
	v_pk_add_f32 v[16:17], v[16:17], v[60:61]
	s_waitcnt vmcnt(3)
	v_pk_add_f32 v[14:15], v[14:15], v[62:63]
	v_pk_add_f32 v[16:17], v[16:17], v[64:65]
	s_waitcnt vmcnt(2)
	v_pk_add_f32 v[2:3], v[2:3], v[76:77]
	v_pk_add_f32 v[4:5], v[4:5], v[78:79]
	s_waitcnt vmcnt(1)
	v_pk_add_f32 v[14:15], v[14:15], v[66:67]
	v_pk_add_f32 v[16:17], v[16:17], v[68:69]
	s_waitcnt vmcnt(0)
	v_pk_add_f32 v[14:15], v[14:15], v[18:19]
	v_pk_add_f32 v[16:17], v[16:17], v[20:21]
